# 128x128 GEMM loops: first-step fragment reads issued right after the barrier, before the LDS-DMA issues
# speedup vs baseline: 1.0270x; 1.0055x over previous
.LBB0_1406:
	s_cmp_lt_u32 s26, 10
	s_cselect_b32 s0, s41, s43
	v_mov_b32_e32 v79, s0
	s_movk_i32 s0, 0x180
	s_cselect_b32 s0, s0, 0x500
	v_mad_i64_i32 v[80:81], s[30:31], s0, v64, 0
	s_cselect_b32 s29, s40, s42
	s_cselect_b32 s30, 0, 0xfffffe80
	v_mov_b32_e32 v78, s29
	s_cselect_b32 s29, 0, -1
	s_add_u32 s30, s10, s30
	v_lshl_add_u64 v[78:79], v[80:81], 1, v[78:79]
	s_addc_u32 s31, s11, s29
	v_lshl_add_u64 v[78:79], s[30:31], 1, v[78:79]
	s_lshl_b32 s29, s28, 14
	s_waitcnt vmcnt(0)
	v_lshl_add_u64 v[82:83], v[78:79], 0, v[68:69]
	s_add_i32 s29, s14, s29
	s_lshl_b32 s0, s0, 5
	s_waitcnt lgkmcnt(0)
	s_barrier
	s_lshl_b32 s98, s27, 14
	v_add_u32_e32 v65, s98, v88
	v_or_b32_e32 v124, s98, v89
	ds_read_b128 v[78:81], v65
	ds_read_b128 v[92:95], v65 offset:1024
	ds_read_b128 v[96:99], v65 offset:2048
	ds_read_b128 v[100:103], v65 offset:3072
	ds_read_b128 v[104:107], v124
	ds_read_b128 v[108:111], v124 offset:1024
	ds_read_b128 v[112:115], v124 offset:2048
	ds_read_b128 v[116:119], v124 offset:3072
	v_lshl_add_u64 v[128:129], v[82:83], 0, s[4:5]
	s_mov_b32 m0, s29
	v_lshl_add_u64 v[120:121], v[82:83], 0, s[0:1]
	global_load_lds_dwordx4 v[128:129], off
	v_lshl_add_u64 v[128:129], v[120:121], 0, s[4:5]
	s_add_i32 m0, s29, 0x400
	v_lshl_add_u64 v[122:123], v[66:67], 0, s[12:13]
	global_load_lds_dwordx4 v[128:129], off
	s_add_i32 m0, s29, 0x2000
	v_lshl_add_u64 v[128:129], v[122:123], 0, s[4:5]
	s_lshl_b32 s0, s27, 14
	global_load_lds_dwordx4 v[128:129], off
	s_add_i32 m0, s29, 0x2400
	s_add_i32 s0, s27, 1
	s_cmp_lg_u32 s27, 3
	s_mov_b64 s[30:31], 0x8080
	s_cselect_b32 s27, s0, 0
	s_add_i32 s0, s28, 1
	v_lshl_add_u64 v[128:129], v[122:123], 0, s[30:31]
	s_cmp_lg_u32 s28, 3
	global_load_lds_dwordx4 v[128:129], off
	s_cselect_b32 s0, s0, 0
	s_waitcnt lgkmcnt(0)
	s_lshl_b32 s28, s0, 14
	s_add_i32 s30, s14, s28
	v_mfma_f32_16x16x32_bf16 v[60:63], v[104:107], v[78:81], v[60:63]
	v_mfma_f32_16x16x32_bf16 v[56:59], v[108:111], v[78:81], v[56:59]
	s_mov_b32 m0, s30
	s_mov_b64 s[28:29], 0x80c0
	s_add_i32 s26, s26, 2
	v_mfma_f32_16x16x32_bf16 v[52:55], v[112:115], v[78:81], v[52:55]
	v_mfma_f32_16x16x32_bf16 v[48:51], v[116:119], v[78:81], v[48:51]
	v_lshl_add_u64 v[78:79], v[82:83], 0, s[6:7]
	global_load_lds_dwordx4 v[78:79], off
	v_lshl_add_u64 v[78:79], v[120:121], 0, s[6:7]
	s_add_i32 m0, s30, 0x400
	v_mfma_f32_16x16x32_bf16 v[44:47], v[104:107], v[92:95], v[44:47]
	global_load_lds_dwordx4 v[78:79], off
	s_add_i32 m0, s30, 0x2000
	v_lshl_add_u64 v[78:79], v[122:123], 0, s[6:7]
	global_load_lds_dwordx4 v[78:79], off
	v_lshl_add_u64 v[78:79], v[122:123], 0, s[28:29]
	s_add_i32 m0, s30, 0x2400
	s_lshl_b32 s28, s27, 14
	global_load_lds_dwordx4 v[78:79], off
	v_add_u32_e32 v65, s28, v88
	v_or_b32_e32 v82, s28, v89
	s_add_i32 s28, s27, 1
	v_mfma_f32_16x16x32_bf16 v[40:43], v[108:111], v[92:95], v[40:43]
	s_cmp_lg_u32 s27, 3
	s_cselect_b32 s27, s28, 0
	s_add_i32 s28, s0, 1
	v_mfma_f32_16x16x32_bf16 v[36:39], v[112:115], v[92:95], v[36:39]
	s_cmp_lg_u32 s0, 3
	s_cselect_b32 s28, s28, 0
	s_add_u32 s12, s12, 0x80
	v_mfma_f32_16x16x32_bf16 v[32:35], v[116:119], v[92:95], v[32:35]
	s_addc_u32 s13, s13, 0
	s_add_u32 s10, s10, 64
	s_addc_u32 s11, s11, 0
	v_mfma_f32_16x16x32_bf16 v[28:31], v[104:107], v[96:99], v[28:31]
	s_cmpk_eq_i32 s12, 0x780
	v_mfma_f32_16x16x32_bf16 v[24:27], v[108:111], v[96:99], v[24:27]
	v_mfma_f32_16x16x32_bf16 v[20:23], v[112:115], v[96:99], v[20:23]
	v_mfma_f32_16x16x32_bf16 v[16:19], v[116:119], v[96:99], v[16:19]
	v_mfma_f32_16x16x32_bf16 v[12:15], v[104:107], v[100:103], v[12:15]
	v_mfma_f32_16x16x32_bf16 v[8:11], v[108:111], v[100:103], v[8:11]
	v_mfma_f32_16x16x32_bf16 v[4:7], v[112:115], v[100:103], v[4:7]
	v_mfma_f32_16x16x32_bf16 v[0:3], v[116:119], v[100:103], v[0:3]
	ds_read_b128 v[78:81], v65
	ds_read_b128 v[92:95], v65 offset:1024
	ds_read_b128 v[96:99], v65 offset:2048
	ds_read_b128 v[100:103], v65 offset:3072
	ds_read_b128 v[104:107], v82
	ds_read_b128 v[108:111], v82 offset:1024
	ds_read_b128 v[112:115], v82 offset:2048
	ds_read_b128 v[116:119], v82 offset:3072
	s_waitcnt lgkmcnt(0)
	s_nop 0
	v_mfma_f32_16x16x32_bf16 v[60:63], v[104:107], v[78:81], v[60:63]
	v_mfma_f32_16x16x32_bf16 v[56:59], v[108:111], v[78:81], v[56:59]
	v_mfma_f32_16x16x32_bf16 v[52:55], v[112:115], v[78:81], v[52:55]
	v_mfma_f32_16x16x32_bf16 v[48:51], v[116:119], v[78:81], v[48:51]
	v_mfma_f32_16x16x32_bf16 v[44:47], v[104:107], v[92:95], v[44:47]
	v_mfma_f32_16x16x32_bf16 v[40:43], v[108:111], v[92:95], v[40:43]
	v_mfma_f32_16x16x32_bf16 v[36:39], v[112:115], v[92:95], v[36:39]
	v_mfma_f32_16x16x32_bf16 v[32:35], v[116:119], v[92:95], v[32:35]
	v_mfma_f32_16x16x32_bf16 v[28:31], v[104:107], v[96:99], v[28:31]
	v_mfma_f32_16x16x32_bf16 v[24:27], v[108:111], v[96:99], v[24:27]
	v_mfma_f32_16x16x32_bf16 v[20:23], v[112:115], v[96:99], v[20:23]
	v_mfma_f32_16x16x32_bf16 v[16:19], v[116:119], v[96:99], v[16:19]
	v_mfma_f32_16x16x32_bf16 v[12:15], v[104:107], v[100:103], v[12:15]
	v_mfma_f32_16x16x32_bf16 v[8:11], v[108:111], v[100:103], v[8:11]
	v_mfma_f32_16x16x32_bf16 v[4:7], v[112:115], v[100:103], v[4:7]
	v_mfma_f32_16x16x32_bf16 v[0:3], v[116:119], v[100:103], v[0:3]
	s_cbranch_scc0 .LBB0_1406
	s_waitcnt vmcnt(4)
	s_waitcnt lgkmcnt(0)
	s_barrier
	ds_read_b128 v[64:67], v88 offset:32768
	ds_read_b128 v[78:81], v88 offset:33792
	ds_read_b128 v[92:95], v88 offset:34816
	ds_read_b128 v[96:99], v88 offset:35840
	ds_read_b128 v[100:103], v89 offset:32768
	ds_read_b128 v[104:107], v89 offset:33792
	ds_read_b128 v[108:111], v89 offset:34816
	ds_read_b128 v[112:115], v89 offset:35840
	s_waitcnt lgkmcnt(0)
	s_waitcnt vmcnt(0)
	s_waitcnt lgkmcnt(0)
	s_barrier
	v_mfma_f32_16x16x32_bf16 v[56:59], v[104:107], v[64:67], v[56:59]
	s_movk_i32 s0, 0xfff
	v_readlane_b32 s36, v241, 1
	v_mfma_f32_16x16x32_bf16 v[40:43], v[104:107], v[78:81], v[40:43]
	v_readlane_b32 s44, v241, 9
	v_readlane_b32 s45, v241, 10
	s_add_i32 s2, s2, s3
	v_mfma_f32_16x16x32_bf16 v[24:27], v[104:107], v[92:95], v[24:27]
	s_add_i32 s15, s15, s16
	s_cmpk_gt_i32 s2, 0x9f
	v_readlane_b32 s37, v241, 2
	v_mfma_f32_16x16x32_bf16 v[52:55], v[108:111], v[64:67], v[52:55]
	v_readlane_b32 s38, v241, 3
	v_readlane_b32 s39, v241, 4
	v_readlane_b32 s40, v241, 5
	v_mfma_f32_16x16x32_bf16 v[36:39], v[108:111], v[78:81], v[36:39]
	v_readlane_b32 s41, v241, 6
	v_readlane_b32 s42, v241, 7
	v_readlane_b32 s43, v241, 8
	v_mfma_f32_16x16x32_bf16 v[20:23], v[108:111], v[92:95], v[20:23]
	v_readlane_b32 s46, v241, 11
	v_readlane_b32 s47, v241, 12
	v_readlane_b32 s48, v241, 13
	v_mfma_f32_16x16x32_bf16 v[60:63], v[100:103], v[64:67], v[60:63]
	v_readlane_b32 s49, v241, 14
	v_readlane_b32 s50, v241, 15
	v_readlane_b32 s51, v241, 16
	v_mfma_f32_16x16x32_bf16 v[48:51], v[112:115], v[64:67], v[48:51]
	v_mfma_f32_16x16x32_bf16 v[44:47], v[100:103], v[78:81], v[44:47]
	v_mfma_f32_16x16x32_bf16 v[32:35], v[112:115], v[78:81], v[32:35]
	v_mfma_f32_16x16x32_bf16 v[28:31], v[100:103], v[92:95], v[28:31]
	v_mfma_f32_16x16x32_bf16 v[16:19], v[112:115], v[92:95], v[16:19]
	v_mfma_f32_16x16x32_bf16 v[12:15], v[100:103], v[96:99], v[12:15]
	v_mfma_f32_16x16x32_bf16 v[8:11], v[104:107], v[96:99], v[8:11]
	v_mfma_f32_16x16x32_bf16 v[4:7], v[108:111], v[96:99], v[4:7]
	v_mfma_f32_16x16x32_bf16 v[0:3], v[112:115], v[96:99], v[0:3]
	ds_read_b128 v[64:67], v88 offset:49152
	ds_read_b128 v[78:81], v88 offset:50176
	ds_read_b128 v[92:95], v88 offset:51200
	ds_read_b128 v[96:99], v88 offset:52224
	ds_read_b128 v[100:103], v89 offset:49152
	ds_read_b128 v[104:107], v89 offset:50176
	ds_read_b128 v[108:111], v89 offset:51200
	ds_read_b128 v[112:115], v89 offset:52224
	s_waitcnt lgkmcnt(0)
	s_waitcnt lgkmcnt(0)
	s_barrier
	v_mfma_f32_16x16x32_bf16 v[120:123], v[104:107], v[64:67], v[56:59]
	v_mfma_f32_16x16x32_bf16 v[56:59], v[104:107], v[78:81], v[40:43]
	v_mfma_f32_16x16x32_bf16 v[40:43], v[104:107], v[92:95], v[24:27]
	s_nop 2
	v_add_u32_e32 v24, s24, v86
	v_mfma_f32_16x16x32_bf16 v[124:127], v[108:111], v[64:67], v[52:55]
	v_cmp_lt_i32_e32 vcc, s0, v24
	s_movk_i32 s0, 0x6000
	v_mfma_f32_16x16x32_bf16 v[52:55], v[108:111], v[78:81], v[36:39]
	v_mfma_f32_16x16x32_bf16 v[36:39], v[108:111], v[92:95], v[20:23]
	s_nop 2
	v_add_u32_e32 v21, 0xfffff000, v24
	v_lshrrev_b32_e32 v21, 12, v21
	v_add_u32_e32 v21, 1, v21
	v_or_b32_e32 v20, s25, v87
	v_cndmask_b32_e32 v21, 0, v21, vcc
	v_mad_u64_u32 v[22:23], s[10:11], v21, s0, v[74:75]
	v_ashrrev_i32_e32 v21, 31, v20
	v_mfma_f32_16x16x32_bf16 v[116:119], v[100:103], v[64:67], v[60:63]
	s_mov_b64 s[10:11], 0x2000
	s_movk_i32 s0, 0x2000
	v_mfma_f32_16x16x32_bf16 v[64:67], v[112:115], v[64:67], v[48:51]
	v_mfma_f32_16x16x32_bf16 v[60:63], v[100:103], v[78:81], v[44:47]
	v_mfma_f32_16x16x32_bf16 v[48:51], v[112:115], v[78:81], v[32:35]
	v_lshlrev_b64 v[78:79], 2, v[20:21]
	v_lshl_add_u64 v[20:21], v[22:23], 0, v[78:79]
	v_lshl_add_u64 v[20:21], v[20:21], 0, v[76:77]
	v_lshl_add_u64 v[22:23], v[20:21], 0, s[10:11]
	v_add_co_u32_e32 v20, vcc, s0, v20
	v_mfma_f32_16x16x32_bf16 v[44:47], v[100:103], v[92:95], v[28:31]
	s_nop 0
	v_addc_co_u32_e32 v21, vcc, 0, v21, vcc
	v_mfma_f32_16x16x32_bf16 v[16:19], v[112:115], v[92:95], v[16:19]
	v_or_b32_e32 v92, v24, v84
	v_or_b32_e32 v82, 32, v92
	v_or_b32_e32 v80, 48, v92
	v_mfma_f32_16x16x32_bf16 v[12:15], v[100:103], v[96:99], v[12:15]
	global_load_dwordx4 v[32:35], v[20:21], off
	global_load_dwordx4 v[28:31], v[22:23], off offset:64
	global_load_dwordx4 v[24:27], v[22:23], off offset:128
	s_nop 0
	global_load_dwordx4 v[20:23], v[22:23], off offset:192
	v_mfma_f32_16x16x32_bf16 v[8:11], v[104:107], v[96:99], v[8:11]
	v_mfma_f32_16x16x32_bf16 v[4:7], v[108:111], v[96:99], v[4:7]
	v_mfma_f32_16x16x32_bf16 v[0:3], v[112:115], v[96:99], v[0:3]
	v_or_b32_e32 v96, 16, v92
	s_nop 0
	v_mov_b32_e32 v194, v92
	v_ashrrev_i32_e32 v195, 31, v92
	v_lshlrev_b64 v[194:195], 12, v[194:195]
	v_lshl_add_u64 v[194:195], s[44:45], 0, v[194:195]
	v_lshl_add_u64 v[194:195], v[194:195], 0, v[78:79]
	v_lshl_add_u64 v[194:195], v[194:195], 0, v[76:77]
	v_mov_b32_e32 v196, v96
	v_ashrrev_i32_e32 v197, 31, v96
	v_lshlrev_b64 v[196:197], 12, v[196:197]
	v_lshl_add_u64 v[196:197], s[44:45], 0, v[196:197]
	v_lshl_add_u64 v[196:197], v[196:197], 0, v[78:79]
	v_lshl_add_u64 v[196:197], v[196:197], 0, v[76:77]
	v_mov_b32_e32 v198, v82
	v_ashrrev_i32_e32 v199, 31, v82
	v_lshlrev_b64 v[198:199], 12, v[198:199]
	v_lshl_add_u64 v[198:199], s[44:45], 0, v[198:199]
	v_lshl_add_u64 v[198:199], v[198:199], 0, v[78:79]
	v_lshl_add_u64 v[198:199], v[198:199], 0, v[76:77]
	v_mov_b32_e32 v200, v80
	v_ashrrev_i32_e32 v201, 31, v80
	v_lshlrev_b64 v[200:201], 12, v[200:201]
	v_lshl_add_u64 v[200:201], s[44:45], 0, v[200:201]
	v_lshl_add_u64 v[200:201], v[200:201], 0, v[78:79]
	v_lshl_add_u64 v[200:201], v[200:201], 0, v[76:77]
	global_load_dwordx4 v[130:133], v[194:195], off
	global_load_dwordx4 v[134:137], v[194:195], off offset:64
	global_load_dwordx4 v[138:141], v[194:195], off offset:128
	global_load_dwordx4 v[142:145], v[194:195], off offset:192
	global_load_dwordx4 v[146:149], v[196:197], off
	global_load_dwordx4 v[150:153], v[196:197], off offset:64
	global_load_dwordx4 v[154:157], v[196:197], off offset:128
	global_load_dwordx4 v[158:161], v[196:197], off offset:192
	global_load_dwordx4 v[162:165], v[198:199], off
	global_load_dwordx4 v[166:169], v[198:199], off offset:64
	global_load_dwordx4 v[170:173], v[198:199], off offset:128
	global_load_dwordx4 v[174:177], v[198:199], off offset:192
	global_load_dwordx4 v[178:181], v[200:201], off
	global_load_dwordx4 v[182:185], v[200:201], off offset:64
	global_load_dwordx4 v[186:189], v[200:201], off offset:128
	global_load_dwordx4 v[190:193], v[200:201], off offset:192
	s_waitcnt vmcnt(15)
	v_pk_mul_f32 v[130:131], v[130:131], s[8:9] op_sel_hi:[1,0]
	v_pk_mul_f32 v[132:133], v[132:133], s[8:9] op_sel_hi:[1,0]
	v_pk_fma_f32 v[130:131], v[116:117], v[32:33], v[130:131]
	v_pk_fma_f32 v[132:133], v[118:119], v[34:35], v[132:133]
	global_store_dwordx4 v[194:195], v[130:133], off
	s_waitcnt vmcnt(15)
	v_pk_mul_f32 v[134:135], v[134:135], s[8:9] op_sel_hi:[1,0]
	v_pk_mul_f32 v[136:137], v[136:137], s[8:9] op_sel_hi:[1,0]
	v_pk_fma_f32 v[134:135], v[120:121], v[28:29], v[134:135]
	v_pk_fma_f32 v[136:137], v[122:123], v[30:31], v[136:137]
	global_store_dwordx4 v[194:195], v[134:137], off offset:64
	s_waitcnt vmcnt(15)
	v_pk_mul_f32 v[138:139], v[138:139], s[8:9] op_sel_hi:[1,0]
	v_pk_mul_f32 v[140:141], v[140:141], s[8:9] op_sel_hi:[1,0]
	v_pk_fma_f32 v[138:139], v[124:125], v[24:25], v[138:139]
	v_pk_fma_f32 v[140:141], v[126:127], v[26:27], v[140:141]
	global_store_dwordx4 v[194:195], v[138:141], off offset:128
	s_waitcnt vmcnt(15)
	v_pk_mul_f32 v[142:143], v[142:143], s[8:9] op_sel_hi:[1,0]
	v_pk_fma_f32 v[64:65], v[64:65], v[20:21], v[142:143]
	v_pk_mul_f32 v[142:143], v[144:145], s[8:9] op_sel_hi:[1,0]
	v_pk_fma_f32 v[66:67], v[66:67], v[22:23], v[142:143]
	global_store_dwordx4 v[194:195], v[64:67], off offset:192
	s_waitcnt vmcnt(15)
	v_pk_mul_f32 v[146:147], v[146:147], s[8:9] op_sel_hi:[1,0]
	v_pk_fma_f32 v[60:61], v[60:61], v[32:33], v[146:147]
	v_pk_mul_f32 v[146:147], v[148:149], s[8:9] op_sel_hi:[1,0]
	v_pk_fma_f32 v[62:63], v[62:63], v[34:35], v[146:147]
	global_store_dwordx4 v[196:197], v[60:63], off
	s_waitcnt vmcnt(15)
	v_pk_mul_f32 v[150:151], v[150:151], s[8:9] op_sel_hi:[1,0]
	v_pk_fma_f32 v[56:57], v[56:57], v[28:29], v[150:151]
	v_pk_mul_f32 v[150:151], v[152:153], s[8:9] op_sel_hi:[1,0]
	v_pk_fma_f32 v[58:59], v[58:59], v[30:31], v[150:151]
	global_store_dwordx4 v[196:197], v[56:59], off offset:64
	s_waitcnt vmcnt(15)
	v_pk_mul_f32 v[154:155], v[154:155], s[8:9] op_sel_hi:[1,0]
	v_pk_fma_f32 v[52:53], v[52:53], v[24:25], v[154:155]
	v_pk_mul_f32 v[154:155], v[156:157], s[8:9] op_sel_hi:[1,0]
	v_pk_fma_f32 v[54:55], v[54:55], v[26:27], v[154:155]
	global_store_dwordx4 v[196:197], v[52:55], off offset:128
	s_waitcnt vmcnt(15)
	v_pk_mul_f32 v[158:159], v[158:159], s[8:9] op_sel_hi:[1,0]
	v_pk_fma_f32 v[48:49], v[48:49], v[20:21], v[158:159]
	v_pk_mul_f32 v[158:159], v[160:161], s[8:9] op_sel_hi:[1,0]
	v_pk_fma_f32 v[50:51], v[50:51], v[22:23], v[158:159]
	global_store_dwordx4 v[196:197], v[48:51], off offset:192
	s_waitcnt vmcnt(15)
	v_pk_mul_f32 v[162:163], v[162:163], s[8:9] op_sel_hi:[1,0]
	v_pk_fma_f32 v[44:45], v[44:45], v[32:33], v[162:163]
	v_pk_mul_f32 v[162:163], v[164:165], s[8:9] op_sel_hi:[1,0]
	v_pk_fma_f32 v[46:47], v[46:47], v[34:35], v[162:163]
	global_store_dwordx4 v[198:199], v[44:47], off
	s_waitcnt vmcnt(15)
	v_pk_mul_f32 v[166:167], v[166:167], s[8:9] op_sel_hi:[1,0]
	v_pk_fma_f32 v[40:41], v[40:41], v[28:29], v[166:167]
	v_pk_mul_f32 v[166:167], v[168:169], s[8:9] op_sel_hi:[1,0]
	v_pk_fma_f32 v[42:43], v[42:43], v[30:31], v[166:167]
	global_store_dwordx4 v[198:199], v[40:43], off offset:64
	s_waitcnt vmcnt(15)
	v_pk_mul_f32 v[170:171], v[170:171], s[8:9] op_sel_hi:[1,0]
	v_pk_fma_f32 v[36:37], v[36:37], v[24:25], v[170:171]
	v_pk_mul_f32 v[170:171], v[172:173], s[8:9] op_sel_hi:[1,0]
	v_pk_fma_f32 v[38:39], v[38:39], v[26:27], v[170:171]
	global_store_dwordx4 v[198:199], v[36:39], off offset:128
	s_waitcnt vmcnt(15)
	v_pk_mul_f32 v[174:175], v[174:175], s[8:9] op_sel_hi:[1,0]
	v_pk_fma_f32 v[16:17], v[16:17], v[20:21], v[174:175]
	v_pk_mul_f32 v[174:175], v[176:177], s[8:9] op_sel_hi:[1,0]
	v_pk_fma_f32 v[18:19], v[18:19], v[22:23], v[174:175]
	global_store_dwordx4 v[198:199], v[16:19], off offset:192
	s_waitcnt vmcnt(15)
	v_pk_mul_f32 v[178:179], v[178:179], s[8:9] op_sel_hi:[1,0]
	v_pk_fma_f32 v[12:13], v[12:13], v[32:33], v[178:179]
	v_pk_mul_f32 v[178:179], v[180:181], s[8:9] op_sel_hi:[1,0]
	v_pk_fma_f32 v[14:15], v[14:15], v[34:35], v[178:179]
	global_store_dwordx4 v[200:201], v[12:15], off
	s_waitcnt vmcnt(15)
	v_pk_mul_f32 v[182:183], v[182:183], s[8:9] op_sel_hi:[1,0]
	v_pk_fma_f32 v[8:9], v[8:9], v[28:29], v[182:183]
	v_pk_mul_f32 v[182:183], v[184:185], s[8:9] op_sel_hi:[1,0]
	v_pk_fma_f32 v[10:11], v[10:11], v[30:31], v[182:183]
	global_store_dwordx4 v[200:201], v[8:11], off offset:64
	s_waitcnt vmcnt(15)
	v_pk_mul_f32 v[186:187], v[186:187], s[8:9] op_sel_hi:[1,0]
	v_pk_fma_f32 v[4:5], v[4:5], v[24:25], v[186:187]
	v_pk_mul_f32 v[186:187], v[188:189], s[8:9] op_sel_hi:[1,0]
	v_pk_fma_f32 v[6:7], v[6:7], v[26:27], v[186:187]
	global_store_dwordx4 v[200:201], v[4:7], off offset:128
	s_waitcnt vmcnt(15)
	v_pk_mul_f32 v[190:191], v[190:191], s[8:9] op_sel_hi:[1,0]
	v_pk_fma_f32 v[0:1], v[0:1], v[20:21], v[190:191]
	v_pk_mul_f32 v[190:191], v[192:193], s[8:9] op_sel_hi:[1,0]
	v_pk_fma_f32 v[2:3], v[2:3], v[22:23], v[190:191]
	global_store_dwordx4 v[200:201], v[0:3], off offset:192
	s_cbranch_scc0 .LBB0_1405

.LBB0_1577:
	s_lshl_b32 s36, s35, 14
	s_waitcnt vmcnt(0)
	v_lshl_add_u64 v[80:81], v[66:67], 0, s[16:17]
	s_add_i32 s36, s19, s36
	s_waitcnt lgkmcnt(0)
	s_barrier
	s_lshl_b32 s98, s34, 14
	v_add_u32_e32 v120, s98, v86
	v_or_b32_e32 v121, s98, v87
	ds_read_b128 v[76:79], v120
	ds_read_b128 v[90:93], v120 offset:1024
	ds_read_b128 v[94:97], v120 offset:2048
	ds_read_b128 v[98:101], v120 offset:3072
	ds_read_b128 v[102:105], v121
	ds_read_b128 v[106:109], v121 offset:1024
	ds_read_b128 v[110:113], v121 offset:2048
	ds_read_b128 v[114:117], v121 offset:3072
	v_lshl_add_u64 v[126:127], v[80:81], 0, s[6:7]
	s_mov_b32 m0, s36
	v_lshl_add_u64 v[118:119], v[64:65], 0, s[16:17]
	global_load_lds_dwordx4 v[126:127], off
	v_lshl_add_u64 v[126:127], v[80:81], 0, s[8:9]
	s_add_i32 m0, s36, 0x400
	s_nop 0
	global_load_lds_dwordx4 v[126:127], off
	s_add_i32 m0, s36, 0x2000
	v_lshl_add_u64 v[126:127], v[118:119], 0, s[6:7]
	global_load_lds_dwordx4 v[126:127], off
	s_add_i32 m0, s36, 0x2400
	s_lshl_b32 s36, s34, 14
	s_add_i32 s36, s34, 1
	s_cmp_lg_u32 s34, 3
	s_cselect_b32 s34, s36, 0
	s_add_i32 s36, s35, 1
	v_lshl_add_u64 v[126:127], v[118:119], 0, s[8:9]
	s_cmp_lg_u32 s35, 3
	global_load_lds_dwordx4 v[126:127], off
	s_cselect_b32 s35, s36, 0
	s_waitcnt lgkmcnt(0)
	s_lshl_b32 s36, s35, 14
	s_add_i32 s36, s19, s36
	v_mfma_f32_16x16x32_bf16 v[60:63], v[102:105], v[76:79], v[60:63]
	v_mfma_f32_16x16x32_bf16 v[56:59], v[106:109], v[76:79], v[56:59]
	s_mov_b32 m0, s36
	v_mfma_f32_16x16x32_bf16 v[52:55], v[110:113], v[76:79], v[52:55]
	v_mfma_f32_16x16x32_bf16 v[48:51], v[114:117], v[76:79], v[48:51]
	v_lshl_add_u64 v[76:77], v[80:81], 0, s[10:11]
	global_load_lds_dwordx4 v[76:77], off
	v_lshl_add_u64 v[76:77], v[80:81], 0, s[12:13]
	s_add_i32 m0, s36, 0x400
	v_mfma_f32_16x16x32_bf16 v[44:47], v[102:105], v[90:93], v[44:47]
	global_load_lds_dwordx4 v[76:77], off
	s_add_i32 m0, s36, 0x2000
	v_lshl_add_u64 v[76:77], v[118:119], 0, s[10:11]
	global_load_lds_dwordx4 v[76:77], off
	v_lshl_add_u64 v[76:77], v[118:119], 0, s[12:13]
	s_add_i32 m0, s36, 0x2400
	v_mfma_f32_16x16x32_bf16 v[40:43], v[106:109], v[90:93], v[40:43]
	global_load_lds_dwordx4 v[76:77], off
	s_lshl_b32 s36, s34, 14
	v_mfma_f32_16x16x32_bf16 v[36:39], v[110:113], v[90:93], v[36:39]
	v_add_u32_e32 v80, s36, v86
	v_or_b32_e32 v81, s36, v87
	s_add_i32 s36, s34, 1
	v_mfma_f32_16x16x32_bf16 v[32:35], v[114:117], v[90:93], v[32:35]
	s_cmp_lg_u32 s34, 3
	s_cselect_b32 s34, s36, 0
	s_add_i32 s36, s35, 1
	v_mfma_f32_16x16x32_bf16 v[28:31], v[102:105], v[94:97], v[28:31]
	s_cmp_lg_u32 s35, 3
	s_cselect_b32 s35, s36, 0
	s_add_u32 s16, s16, 0x80
	v_mfma_f32_16x16x32_bf16 v[24:27], v[106:109], v[94:97], v[24:27]
	s_addc_u32 s17, s17, 0
	s_cmpk_eq_i32 s16, 0x1580
	v_mfma_f32_16x16x32_bf16 v[20:23], v[110:113], v[94:97], v[20:23]
	v_mfma_f32_16x16x32_bf16 v[16:19], v[114:117], v[94:97], v[16:19]
	v_mfma_f32_16x16x32_bf16 v[12:15], v[102:105], v[98:101], v[12:15]
	v_mfma_f32_16x16x32_bf16 v[8:11], v[106:109], v[98:101], v[8:11]
	v_mfma_f32_16x16x32_bf16 v[4:7], v[110:113], v[98:101], v[4:7]
	v_mfma_f32_16x16x32_bf16 v[0:3], v[114:117], v[98:101], v[0:3]
	ds_read_b128 v[76:79], v80
	ds_read_b128 v[90:93], v80 offset:1024
	ds_read_b128 v[94:97], v80 offset:2048
	ds_read_b128 v[98:101], v80 offset:3072
	ds_read_b128 v[102:105], v81
	ds_read_b128 v[106:109], v81 offset:1024
	ds_read_b128 v[110:113], v81 offset:2048
	ds_read_b128 v[114:117], v81 offset:3072
	s_waitcnt lgkmcnt(0)
	s_nop 0
	v_mfma_f32_16x16x32_bf16 v[60:63], v[102:105], v[76:79], v[60:63]
	v_mfma_f32_16x16x32_bf16 v[56:59], v[106:109], v[76:79], v[56:59]
	v_mfma_f32_16x16x32_bf16 v[52:55], v[110:113], v[76:79], v[52:55]
	v_mfma_f32_16x16x32_bf16 v[48:51], v[114:117], v[76:79], v[48:51]
	v_mfma_f32_16x16x32_bf16 v[44:47], v[102:105], v[90:93], v[44:47]
	v_mfma_f32_16x16x32_bf16 v[40:43], v[106:109], v[90:93], v[40:43]
	v_mfma_f32_16x16x32_bf16 v[36:39], v[110:113], v[90:93], v[36:39]
	v_mfma_f32_16x16x32_bf16 v[32:35], v[114:117], v[90:93], v[32:35]
	v_mfma_f32_16x16x32_bf16 v[28:31], v[102:105], v[94:97], v[28:31]
	v_mfma_f32_16x16x32_bf16 v[24:27], v[106:109], v[94:97], v[24:27]
	v_mfma_f32_16x16x32_bf16 v[20:23], v[110:113], v[94:97], v[20:23]
	v_mfma_f32_16x16x32_bf16 v[16:19], v[114:117], v[94:97], v[16:19]
	v_mfma_f32_16x16x32_bf16 v[12:15], v[102:105], v[98:101], v[12:15]
	v_mfma_f32_16x16x32_bf16 v[8:11], v[106:109], v[98:101], v[8:11]
	v_mfma_f32_16x16x32_bf16 v[4:7], v[110:113], v[98:101], v[4:7]
	v_mfma_f32_16x16x32_bf16 v[0:3], v[114:117], v[98:101], v[0:3]
	s_cbranch_scc0 .LBB0_1577
	s_waitcnt vmcnt(4)
	s_waitcnt lgkmcnt(0)
	s_barrier
	ds_read_b128 v[64:67], v86 offset:32768
	ds_read_b128 v[76:79], v86 offset:33792
	ds_read_b128 v[90:93], v86 offset:34816
	ds_read_b128 v[94:97], v86 offset:35840
	ds_read_b128 v[98:101], v87 offset:32768
	ds_read_b128 v[102:105], v87 offset:33792
	ds_read_b128 v[106:109], v87 offset:34816
	ds_read_b128 v[110:113], v87 offset:35840
	s_waitcnt lgkmcnt(0)
	s_waitcnt vmcnt(0)
	s_waitcnt lgkmcnt(0)
	s_barrier
	v_mfma_f32_16x16x32_bf16 v[56:59], v[102:105], v[64:67], v[56:59]
	s_movk_i32 s16, 0xfff
	v_readlane_b32 s36, v241, 1
	v_mfma_f32_16x16x32_bf16 v[40:43], v[102:105], v[76:79], v[40:43]
	v_readlane_b32 s44, v241, 9
	v_readlane_b32 s45, v241, 10
	s_add_i32 s2, s2, s3
	v_mfma_f32_16x16x32_bf16 v[24:27], v[102:105], v[90:93], v[24:27]
	s_add_i32 s20, s20, s21
	v_readlane_b32 s37, v241, 2
	v_readlane_b32 s38, v241, 3
	v_mfma_f32_16x16x32_bf16 v[52:55], v[106:109], v[64:67], v[52:55]
	v_readlane_b32 s39, v241, 4
	v_readlane_b32 s40, v241, 5
	v_readlane_b32 s41, v241, 6
	v_mfma_f32_16x16x32_bf16 v[36:39], v[106:109], v[76:79], v[36:39]
	v_readlane_b32 s42, v241, 7
	v_readlane_b32 s43, v241, 8
	v_readlane_b32 s46, v241, 11
	v_mfma_f32_16x16x32_bf16 v[20:23], v[106:109], v[90:93], v[20:23]
	v_readlane_b32 s47, v241, 12
	v_readlane_b32 s48, v241, 13
	v_readlane_b32 s49, v241, 14
	v_mfma_f32_16x16x32_bf16 v[60:63], v[98:101], v[64:67], v[60:63]
	v_readlane_b32 s50, v241, 15
	v_readlane_b32 s51, v241, 16
	v_mfma_f32_16x16x32_bf16 v[48:51], v[110:113], v[64:67], v[48:51]
	v_mfma_f32_16x16x32_bf16 v[44:47], v[98:101], v[76:79], v[44:47]
	v_mfma_f32_16x16x32_bf16 v[32:35], v[110:113], v[76:79], v[32:35]
	v_mfma_f32_16x16x32_bf16 v[28:31], v[98:101], v[90:93], v[28:31]
	v_mfma_f32_16x16x32_bf16 v[16:19], v[110:113], v[90:93], v[16:19]
	v_mfma_f32_16x16x32_bf16 v[12:15], v[98:101], v[94:97], v[12:15]
	v_mfma_f32_16x16x32_bf16 v[8:11], v[102:105], v[94:97], v[8:11]
	v_mfma_f32_16x16x32_bf16 v[4:7], v[106:109], v[94:97], v[4:7]
	v_mfma_f32_16x16x32_bf16 v[0:3], v[110:113], v[94:97], v[0:3]
	ds_read_b128 v[64:67], v86 offset:49152
	ds_read_b128 v[76:79], v86 offset:50176
	ds_read_b128 v[90:93], v86 offset:51200
	ds_read_b128 v[94:97], v86 offset:52224
	ds_read_b128 v[98:101], v87 offset:49152
	ds_read_b128 v[102:105], v87 offset:50176
	ds_read_b128 v[106:109], v87 offset:51200
	ds_read_b128 v[110:113], v87 offset:52224
	s_waitcnt lgkmcnt(0)
	s_waitcnt lgkmcnt(0)
	s_barrier
	v_mfma_f32_16x16x32_bf16 v[118:121], v[102:105], v[64:67], v[56:59]
	v_mfma_f32_16x16x32_bf16 v[56:59], v[102:105], v[76:79], v[40:43]
	v_mfma_f32_16x16x32_bf16 v[40:43], v[102:105], v[90:93], v[24:27]
	s_nop 2
	v_add_u32_e32 v24, s31, v84
	v_mfma_f32_16x16x32_bf16 v[122:125], v[106:109], v[64:67], v[52:55]
	v_cmp_lt_i32_e32 vcc, s16, v24
	s_movk_i32 s16, 0x6000
	v_mfma_f32_16x16x32_bf16 v[52:55], v[106:109], v[76:79], v[36:39]
	v_mfma_f32_16x16x32_bf16 v[36:39], v[106:109], v[90:93], v[20:23]
	s_nop 2
	v_add_u32_e32 v21, 0xfffff000, v24
	v_lshrrev_b32_e32 v21, 12, v21
	v_add_u32_e32 v21, 1, v21
	v_or_b32_e32 v20, s33, v85
	v_cndmask_b32_e32 v21, 0, v21, vcc
	v_mad_u64_u32 v[22:23], s[16:17], v21, s16, v[74:75]
	v_ashrrev_i32_e32 v21, 31, v20
	v_mfma_f32_16x16x32_bf16 v[114:117], v[98:101], v[64:67], v[60:63]
	s_mov_b64 s[16:17], 0x5000
	v_mfma_f32_16x16x32_bf16 v[64:67], v[110:113], v[64:67], v[48:51]
	v_mfma_f32_16x16x32_bf16 v[60:63], v[98:101], v[76:79], v[44:47]
	v_mfma_f32_16x16x32_bf16 v[48:51], v[110:113], v[76:79], v[32:35]
	v_lshlrev_b64 v[76:77], 2, v[20:21]
	v_lshl_add_u64 v[20:21], v[22:23], 0, v[76:77]
	v_lshl_add_u64 v[20:21], v[20:21], 0, v[68:69]
	v_lshl_add_u64 v[22:23], v[20:21], 0, s[16:17]
	s_movk_i32 s16, 0x5000
	v_add_co_u32_e32 v20, vcc, s16, v20
	v_mfma_f32_16x16x32_bf16 v[44:47], v[98:101], v[90:93], v[28:31]
	s_nop 0
	v_addc_co_u32_e32 v21, vcc, 0, v21, vcc
	v_mfma_f32_16x16x32_bf16 v[16:19], v[110:113], v[90:93], v[16:19]
	v_or_b32_e32 v90, v24, v82
	v_or_b32_e32 v80, 32, v90
	v_or_b32_e32 v78, 48, v90
	v_mfma_f32_16x16x32_bf16 v[12:15], v[98:101], v[94:97], v[12:15]
	global_load_dwordx4 v[32:35], v[20:21], off
	global_load_dwordx4 v[28:31], v[22:23], off offset:64
	global_load_dwordx4 v[24:27], v[22:23], off offset:128
	s_nop 0
	global_load_dwordx4 v[20:23], v[22:23], off offset:192
	v_mfma_f32_16x16x32_bf16 v[8:11], v[102:105], v[94:97], v[8:11]
	v_mfma_f32_16x16x32_bf16 v[4:7], v[106:109], v[94:97], v[4:7]
	v_mfma_f32_16x16x32_bf16 v[0:3], v[110:113], v[94:97], v[0:3]
	v_or_b32_e32 v94, 16, v90
	s_nop 0
	v_mov_b32_e32 v192, v90
	v_ashrrev_i32_e32 v193, 31, v90
	v_lshlrev_b64 v[192:193], 12, v[192:193]
	v_lshl_add_u64 v[192:193], s[44:45], 0, v[192:193]
	v_lshl_add_u64 v[192:193], v[192:193], 0, v[76:77]
	v_lshl_add_u64 v[192:193], v[192:193], 0, v[68:69]
	v_mov_b32_e32 v194, v94
	v_ashrrev_i32_e32 v195, 31, v94
	v_lshlrev_b64 v[194:195], 12, v[194:195]
	v_lshl_add_u64 v[194:195], s[44:45], 0, v[194:195]
	v_lshl_add_u64 v[194:195], v[194:195], 0, v[76:77]
	v_lshl_add_u64 v[194:195], v[194:195], 0, v[68:69]
	v_mov_b32_e32 v196, v80
	v_ashrrev_i32_e32 v197, 31, v80
	v_lshlrev_b64 v[196:197], 12, v[196:197]
	v_lshl_add_u64 v[196:197], s[44:45], 0, v[196:197]
	v_lshl_add_u64 v[196:197], v[196:197], 0, v[76:77]
	v_lshl_add_u64 v[196:197], v[196:197], 0, v[68:69]
	v_mov_b32_e32 v198, v78
	v_ashrrev_i32_e32 v199, 31, v78
	v_lshlrev_b64 v[198:199], 12, v[198:199]
	v_lshl_add_u64 v[198:199], s[44:45], 0, v[198:199]
	v_lshl_add_u64 v[198:199], v[198:199], 0, v[76:77]
	v_lshl_add_u64 v[198:199], v[198:199], 0, v[68:69]
	global_load_dwordx4 v[128:131], v[192:193], off
	global_load_dwordx4 v[132:135], v[192:193], off offset:64
	global_load_dwordx4 v[136:139], v[192:193], off offset:128
	global_load_dwordx4 v[140:143], v[192:193], off offset:192
	global_load_dwordx4 v[144:147], v[194:195], off
	global_load_dwordx4 v[148:151], v[194:195], off offset:64
	global_load_dwordx4 v[152:155], v[194:195], off offset:128
	global_load_dwordx4 v[156:159], v[194:195], off offset:192
	global_load_dwordx4 v[160:163], v[196:197], off
	global_load_dwordx4 v[164:167], v[196:197], off offset:64
	global_load_dwordx4 v[168:171], v[196:197], off offset:128
	global_load_dwordx4 v[172:175], v[196:197], off offset:192
	global_load_dwordx4 v[176:179], v[198:199], off
	global_load_dwordx4 v[180:183], v[198:199], off offset:64
	global_load_dwordx4 v[184:187], v[198:199], off offset:128
	global_load_dwordx4 v[188:191], v[198:199], off offset:192
	s_waitcnt vmcnt(15)
	v_pk_mul_f32 v[128:129], v[128:129], s[14:15] op_sel_hi:[1,0]
	v_pk_mul_f32 v[130:131], v[130:131], s[14:15] op_sel_hi:[1,0]
	v_pk_fma_f32 v[128:129], v[114:115], v[32:33], v[128:129]
	v_pk_fma_f32 v[130:131], v[116:117], v[34:35], v[130:131]
	global_store_dwordx4 v[192:193], v[128:131], off
	s_waitcnt vmcnt(15)
	v_pk_mul_f32 v[132:133], v[132:133], s[14:15] op_sel_hi:[1,0]
	v_pk_mul_f32 v[134:135], v[134:135], s[14:15] op_sel_hi:[1,0]
	v_pk_fma_f32 v[132:133], v[118:119], v[28:29], v[132:133]
	v_pk_fma_f32 v[134:135], v[120:121], v[30:31], v[134:135]
	global_store_dwordx4 v[192:193], v[132:135], off offset:64
	s_waitcnt vmcnt(15)
	v_pk_mul_f32 v[136:137], v[136:137], s[14:15] op_sel_hi:[1,0]
	v_pk_mul_f32 v[138:139], v[138:139], s[14:15] op_sel_hi:[1,0]
	v_pk_fma_f32 v[136:137], v[122:123], v[24:25], v[136:137]
	v_pk_fma_f32 v[138:139], v[124:125], v[26:27], v[138:139]
	global_store_dwordx4 v[192:193], v[136:139], off offset:128
	s_waitcnt vmcnt(15)
	v_pk_mul_f32 v[140:141], v[140:141], s[14:15] op_sel_hi:[1,0]
	v_pk_fma_f32 v[64:65], v[64:65], v[20:21], v[140:141]
	v_pk_mul_f32 v[140:141], v[142:143], s[14:15] op_sel_hi:[1,0]
	v_pk_fma_f32 v[66:67], v[66:67], v[22:23], v[140:141]
	global_store_dwordx4 v[192:193], v[64:67], off offset:192
	s_waitcnt vmcnt(15)
	v_pk_mul_f32 v[144:145], v[144:145], s[14:15] op_sel_hi:[1,0]
	v_pk_fma_f32 v[60:61], v[60:61], v[32:33], v[144:145]
	v_pk_mul_f32 v[144:145], v[146:147], s[14:15] op_sel_hi:[1,0]
	v_pk_fma_f32 v[62:63], v[62:63], v[34:35], v[144:145]
	global_store_dwordx4 v[194:195], v[60:63], off
	s_waitcnt vmcnt(15)
	v_pk_mul_f32 v[148:149], v[148:149], s[14:15] op_sel_hi:[1,0]
	v_pk_fma_f32 v[56:57], v[56:57], v[28:29], v[148:149]
	v_pk_mul_f32 v[148:149], v[150:151], s[14:15] op_sel_hi:[1,0]
	v_pk_fma_f32 v[58:59], v[58:59], v[30:31], v[148:149]
	global_store_dwordx4 v[194:195], v[56:59], off offset:64
	s_waitcnt vmcnt(15)
	v_pk_mul_f32 v[152:153], v[152:153], s[14:15] op_sel_hi:[1,0]
	v_pk_fma_f32 v[52:53], v[52:53], v[24:25], v[152:153]
	v_pk_mul_f32 v[152:153], v[154:155], s[14:15] op_sel_hi:[1,0]
	v_pk_fma_f32 v[54:55], v[54:55], v[26:27], v[152:153]
	global_store_dwordx4 v[194:195], v[52:55], off offset:128
	s_waitcnt vmcnt(15)
	v_pk_mul_f32 v[156:157], v[156:157], s[14:15] op_sel_hi:[1,0]
	v_pk_fma_f32 v[48:49], v[48:49], v[20:21], v[156:157]
	v_pk_mul_f32 v[156:157], v[158:159], s[14:15] op_sel_hi:[1,0]
	v_pk_fma_f32 v[50:51], v[50:51], v[22:23], v[156:157]
	global_store_dwordx4 v[194:195], v[48:51], off offset:192
	s_waitcnt vmcnt(15)
	v_pk_mul_f32 v[160:161], v[160:161], s[14:15] op_sel_hi:[1,0]
	v_pk_fma_f32 v[44:45], v[44:45], v[32:33], v[160:161]
	v_pk_mul_f32 v[160:161], v[162:163], s[14:15] op_sel_hi:[1,0]
	v_pk_fma_f32 v[46:47], v[46:47], v[34:35], v[160:161]
	global_store_dwordx4 v[196:197], v[44:47], off
	s_waitcnt vmcnt(15)
	v_pk_mul_f32 v[164:165], v[164:165], s[14:15] op_sel_hi:[1,0]
	v_pk_fma_f32 v[40:41], v[40:41], v[28:29], v[164:165]
	v_pk_mul_f32 v[164:165], v[166:167], s[14:15] op_sel_hi:[1,0]
	v_pk_fma_f32 v[42:43], v[42:43], v[30:31], v[164:165]
	global_store_dwordx4 v[196:197], v[40:43], off offset:64
	s_waitcnt vmcnt(15)
	v_pk_mul_f32 v[168:169], v[168:169], s[14:15] op_sel_hi:[1,0]
	v_pk_fma_f32 v[36:37], v[36:37], v[24:25], v[168:169]
	v_pk_mul_f32 v[168:169], v[170:171], s[14:15] op_sel_hi:[1,0]
	v_pk_fma_f32 v[38:39], v[38:39], v[26:27], v[168:169]
	global_store_dwordx4 v[196:197], v[36:39], off offset:128
	s_waitcnt vmcnt(15)
	v_pk_mul_f32 v[172:173], v[172:173], s[14:15] op_sel_hi:[1,0]
	v_pk_fma_f32 v[16:17], v[16:17], v[20:21], v[172:173]
	v_pk_mul_f32 v[172:173], v[174:175], s[14:15] op_sel_hi:[1,0]
	v_pk_fma_f32 v[18:19], v[18:19], v[22:23], v[172:173]
	global_store_dwordx4 v[196:197], v[16:19], off offset:192
	s_waitcnt vmcnt(15)
	v_pk_mul_f32 v[176:177], v[176:177], s[14:15] op_sel_hi:[1,0]
	v_pk_fma_f32 v[12:13], v[12:13], v[32:33], v[176:177]
	v_pk_mul_f32 v[176:177], v[178:179], s[14:15] op_sel_hi:[1,0]
	v_pk_fma_f32 v[14:15], v[14:15], v[34:35], v[176:177]
	global_store_dwordx4 v[198:199], v[12:15], off
	s_waitcnt vmcnt(15)
	v_pk_mul_f32 v[180:181], v[180:181], s[14:15] op_sel_hi:[1,0]
	v_pk_fma_f32 v[8:9], v[8:9], v[28:29], v[180:181]
	v_pk_mul_f32 v[180:181], v[182:183], s[14:15] op_sel_hi:[1,0]
	v_pk_fma_f32 v[10:11], v[10:11], v[30:31], v[180:181]
	global_store_dwordx4 v[198:199], v[8:11], off offset:64
	s_waitcnt vmcnt(15)
	v_pk_mul_f32 v[184:185], v[184:185], s[14:15] op_sel_hi:[1,0]
	v_pk_fma_f32 v[4:5], v[4:5], v[24:25], v[184:185]
	v_pk_mul_f32 v[184:185], v[186:187], s[14:15] op_sel_hi:[1,0]
	v_pk_fma_f32 v[6:7], v[6:7], v[26:27], v[184:185]
	global_store_dwordx4 v[198:199], v[4:7], off offset:128
	s_waitcnt vmcnt(15)
	v_pk_mul_f32 v[188:189], v[188:189], s[14:15] op_sel_hi:[1,0]
	v_pk_fma_f32 v[0:1], v[0:1], v[20:21], v[188:189]
	v_pk_mul_f32 v[188:189], v[190:191], s[14:15] op_sel_hi:[1,0]
	s_add_i32 s15, s15, s30
	v_pk_fma_f32 v[2:3], v[2:3], v[22:23], v[188:189]
	s_cmpk_gt_i32 s2, 0x9f
	global_store_dwordx4 v[198:199], v[0:3], off offset:192
	s_cbranch_scc0 .LBB0_1576

.LBB0_3063:
	s_lshl_b32 s41, s39, 14
	s_waitcnt vmcnt(0)
	v_lshl_add_u64 v[116:117], v[74:75], 0, s[18:19]
	s_add_i32 s41, s21, s41
	s_waitcnt lgkmcnt(0)
	s_barrier
	s_lshl_b32 s98, s40, 14
	v_add_u32_e32 v120, s98, v80
	v_or_b32_e32 v121, s98, v81
	ds_read_b128 v[84:87], v120
	ds_read_b128 v[88:91], v120 offset:1024
	ds_read_b128 v[92:95], v120 offset:2048
	ds_read_b128 v[96:99], v120 offset:3072
	ds_read_b128 v[100:103], v121
	ds_read_b128 v[104:107], v121 offset:1024
	ds_read_b128 v[108:111], v121 offset:2048
	ds_read_b128 v[112:115], v121 offset:3072
	v_lshl_add_u64 v[162:163], v[116:117], 0, s[6:7]
	s_mov_b32 m0, s41
	v_lshl_add_u64 v[118:119], v[72:73], 0, s[18:19]
	v_lshl_add_u64 v[164:165], v[116:117], 0, s[8:9]
	global_load_lds_dwordx4 v[162:163], off
	s_add_i32 m0, s41, 0x400
	v_lshl_add_u64 v[166:167], v[118:119], 0, s[6:7]
	global_load_lds_dwordx4 v[164:165], off
	s_add_i32 m0, s41, 0x2000
	s_lshl_b32 s42, s40, 14
	global_load_lds_dwordx4 v[166:167], off
	s_add_i32 m0, s41, 0x2400
	s_add_i32 s41, s40, 1
	s_cmp_lg_u32 s40, 3
	s_cselect_b32 s40, s41, 0
	s_add_i32 s41, s39, 1
	v_lshl_add_u64 v[168:169], v[118:119], 0, s[8:9]
	s_cmp_lg_u32 s39, 3
	global_load_lds_dwordx4 v[168:169], off
	s_cselect_b32 s39, s41, 0
	s_waitcnt lgkmcnt(0)
	s_lshl_b32 s41, s39, 14
	s_add_i32 s41, s21, s41
	v_mfma_f32_16x16x32_bf16 v[60:63], v[100:103], v[84:87], v[60:63]
	v_mfma_f32_16x16x32_bf16 v[56:59], v[104:107], v[84:87], v[56:59]
	s_mov_b32 m0, s41
	v_mfma_f32_16x16x32_bf16 v[52:55], v[108:111], v[84:87], v[52:55]
	v_mfma_f32_16x16x32_bf16 v[48:51], v[112:115], v[84:87], v[48:51]
	v_lshl_add_u64 v[84:85], v[116:117], 0, s[10:11]
	v_lshl_add_u64 v[86:87], v[116:117], 0, s[12:13]
	global_load_lds_dwordx4 v[84:85], off
	s_add_i32 m0, s41, 0x400
	v_mfma_f32_16x16x32_bf16 v[44:47], v[100:103], v[88:91], v[44:47]
	global_load_lds_dwordx4 v[86:87], off
	s_add_i32 m0, s41, 0x2000
	v_mfma_f32_16x16x32_bf16 v[40:43], v[104:107], v[88:91], v[40:43]
	v_mfma_f32_16x16x32_bf16 v[36:39], v[108:111], v[88:91], v[36:39]
	v_mfma_f32_16x16x32_bf16 v[32:35], v[112:115], v[88:91], v[32:35]
	v_lshl_add_u64 v[88:89], v[118:119], 0, s[10:11]
	v_lshl_add_u64 v[90:91], v[118:119], 0, s[12:13]
	global_load_lds_dwordx4 v[88:89], off
	s_add_i32 m0, s41, 0x2400
	v_mfma_f32_16x16x32_bf16 v[28:31], v[100:103], v[92:95], v[28:31]
	global_load_lds_dwordx4 v[90:91], off
	s_lshl_b32 s41, s40, 14
	v_mfma_f32_16x16x32_bf16 v[24:27], v[104:107], v[92:95], v[24:27]
	v_add_u32_e32 v116, s41, v80
	v_or_b32_e32 v117, s41, v81
	s_add_i32 s41, s40, 1
	v_mfma_f32_16x16x32_bf16 v[16:19], v[108:111], v[92:95], v[16:19]
	s_cmp_lg_u32 s40, 3
	s_cselect_b32 s40, s41, 0
	s_add_i32 s41, s39, 1
	v_mfma_f32_16x16x32_bf16 v[12:15], v[112:115], v[92:95], v[12:15]
	s_cmp_lg_u32 s39, 3
	s_cselect_b32 s39, s41, 0
	s_add_u32 s18, s18, 0x80
	v_mfma_f32_16x16x32_bf16 v[8:11], v[100:103], v[96:99], v[8:11]
	s_addc_u32 s19, s19, 0
	s_cmpk_eq_i32 s18, 0x1580
	v_mfma_f32_16x16x32_bf16 v[4:7], v[104:107], v[96:99], v[4:7]
	v_mfma_f32_16x16x32_bf16 v[0:3], v[108:111], v[96:99], v[0:3]
	v_mfma_f32_16x16x32_bf16 v[20:23], v[112:115], v[96:99], v[20:23]
	ds_read_b128 v[84:87], v116
	ds_read_b128 v[88:91], v116 offset:1024
	ds_read_b128 v[92:95], v116 offset:2048
	ds_read_b128 v[96:99], v116 offset:3072
	ds_read_b128 v[100:103], v117
	ds_read_b128 v[104:107], v117 offset:1024
	ds_read_b128 v[108:111], v117 offset:2048
	ds_read_b128 v[112:115], v117 offset:3072
	s_waitcnt lgkmcnt(0)
	s_nop 0
	v_mfma_f32_16x16x32_bf16 v[60:63], v[100:103], v[84:87], v[60:63]
	v_mfma_f32_16x16x32_bf16 v[56:59], v[104:107], v[84:87], v[56:59]
	v_mfma_f32_16x16x32_bf16 v[52:55], v[108:111], v[84:87], v[52:55]
	v_mfma_f32_16x16x32_bf16 v[48:51], v[112:115], v[84:87], v[48:51]
	v_mfma_f32_16x16x32_bf16 v[44:47], v[100:103], v[88:91], v[44:47]
	v_mfma_f32_16x16x32_bf16 v[40:43], v[104:107], v[88:91], v[40:43]
	v_mfma_f32_16x16x32_bf16 v[36:39], v[108:111], v[88:91], v[36:39]
	v_mfma_f32_16x16x32_bf16 v[32:35], v[112:115], v[88:91], v[32:35]
	v_mfma_f32_16x16x32_bf16 v[28:31], v[100:103], v[92:95], v[28:31]
	v_mfma_f32_16x16x32_bf16 v[24:27], v[104:107], v[92:95], v[24:27]
	v_mfma_f32_16x16x32_bf16 v[16:19], v[108:111], v[92:95], v[16:19]
	v_mfma_f32_16x16x32_bf16 v[12:15], v[112:115], v[92:95], v[12:15]
	v_mfma_f32_16x16x32_bf16 v[8:11], v[100:103], v[96:99], v[8:11]
	v_mfma_f32_16x16x32_bf16 v[4:7], v[104:107], v[96:99], v[4:7]
	v_mfma_f32_16x16x32_bf16 v[0:3], v[108:111], v[96:99], v[0:3]
	v_mfma_f32_16x16x32_bf16 v[20:23], v[112:115], v[96:99], v[20:23]
	s_cbranch_scc0 .LBB0_3063
	s_waitcnt vmcnt(4)
	s_waitcnt lgkmcnt(0)
	s_barrier
	ds_read_b128 v[72:75], v80 offset:32768
	ds_read_b128 v[84:87], v80 offset:33792
	ds_read_b128 v[88:91], v80 offset:34816
	ds_read_b128 v[92:95], v80 offset:35840
	ds_read_b128 v[96:99], v81 offset:32768
	ds_read_b128 v[100:103], v81 offset:33792
	ds_read_b128 v[104:107], v81 offset:34816
	ds_read_b128 v[108:111], v81 offset:35840
	s_waitcnt lgkmcnt(0)
	s_waitcnt vmcnt(0)
	s_waitcnt lgkmcnt(0)
	s_barrier
	v_mfma_f32_16x16x32_bf16 v[112:115], v[96:99], v[72:75], v[60:63]
	v_readlane_b32 s40, v241, 1
	v_readlane_b32 s48, v241, 9
	v_mfma_f32_16x16x32_bf16 v[116:119], v[100:103], v[72:75], v[56:59]
	v_readlane_b32 s49, v241, 10
	s_add_i32 s2, s2, s3
	s_add_i32 s22, s22, s23
	v_mfma_f32_16x16x32_bf16 v[120:123], v[104:107], v[72:75], v[52:55]
	v_readlane_b32 s41, v241, 2
	v_readlane_b32 s42, v241, 3
	v_readlane_b32 s43, v241, 4
	v_mfma_f32_16x16x32_bf16 v[124:127], v[108:111], v[72:75], v[48:51]
	v_add_u32_e32 v74, s37, v78
	v_cmp_lt_i32_e32 vcc, s35, v74
	v_readlane_b32 s44, v241, 5
	v_mfma_f32_16x16x32_bf16 v[60:63], v[104:107], v[88:91], v[16:19]
	v_readlane_b32 s45, v241, 6
	v_readlane_b32 s46, v241, 7
	v_readlane_b32 s47, v241, 8
	v_add_u32_e32 v16, 0xfffff000, v74
	v_lshrrev_b32_e32 v16, 12, v16
	v_mfma_f32_16x16x32_bf16 v[152:155], v[100:103], v[88:91], v[24:27]
	v_add_u32_e32 v16, 6, v16
	v_readlane_b32 s50, v241, 11
	v_readlane_b32 s51, v241, 12
	v_or_b32_e32 v24, s38, v79
	v_mfma_f32_16x16x32_bf16 v[56:59], v[108:111], v[88:91], v[12:15]
	v_ashrrev_i32_e32 v25, 31, v24
	v_lshlrev_b64 v[72:73], 2, v[24:25]
	v_readlane_b32 s52, v241, 13
	v_cndmask_b32_e32 v12, 5, v16, vcc
	v_mad_u64_u32 v[12:13], s[18:19], v12, s30, v[70:71]
	v_mfma_f32_16x16x32_bf16 v[48:51], v[96:99], v[92:95], v[8:11]
	v_readlane_b32 s53, v241, 14
	v_readlane_b32 s54, v241, 15
	v_readlane_b32 s55, v241, 16
	v_lshl_add_u64 v[8:9], v[12:13], 0, v[72:73]
	v_lshl_add_u64 v[12:13], v[8:9], 0, v[64:65]
	v_mfma_f32_16x16x32_bf16 v[128:131], v[96:99], v[84:87], v[44:47]
	v_add_co_u32_e32 v18, vcc, s36, v12
	v_lshl_add_u64 v[16:17], v[12:13], 0, s[14:15]
	v_mfma_f32_16x16x32_bf16 v[132:135], v[100:103], v[84:87], v[40:43]
	v_addc_co_u32_e32 v19, vcc, 0, v13, vcc
	v_mfma_f32_16x16x32_bf16 v[136:139], v[104:107], v[84:87], v[36:39]
	v_mfma_f32_16x16x32_bf16 v[84:87], v[108:111], v[84:87], v[32:35]
	v_mfma_f32_16x16x32_bf16 v[140:143], v[96:99], v[88:91], v[28:31]
	ds_read_b128 v[144:147], v80 offset:49152
	ds_read_b128 v[148:151], v80 offset:50176
	ds_read_b128 v[52:55], v80 offset:51200
	ds_read_b128 v[28:31], v80 offset:52224
	ds_read_b128 v[44:47], v81 offset:49152
	ds_read_b128 v[40:43], v81 offset:50176
	ds_read_b128 v[36:39], v81 offset:51200
	ds_read_b128 v[32:35], v81 offset:52224
	s_waitcnt lgkmcnt(0)
	s_waitcnt lgkmcnt(0)
	s_barrier
	v_or_b32_e32 v96, v74, v76
	v_mfma_f32_16x16x32_bf16 v[24:27], v[100:103], v[92:95], v[4:7]
	v_or_b32_e32 v156, 16, v96
	v_or_b32_e32 v158, 32, v96
	v_or_b32_e32 v74, 48, v96
	v_mfma_f32_16x16x32_bf16 v[4:7], v[104:107], v[92:95], v[0:3]
	s_nop 2
	global_load_dwordx4 v[0:3], v[16:17], off offset:64
	global_load_dwordx4 v[12:15], v[16:17], off offset:128
	v_mfma_f32_16x16x32_bf16 v[8:11], v[108:111], v[92:95], v[20:23]
	s_nop 2
	global_load_dwordx4 v[20:23], v[18:19], off
	s_nop 0
	global_load_dwordx4 v[16:19], v[16:17], off offset:192
	s_nop 0
	v_mov_b32_e32 v236, v96
	v_ashrrev_i32_e32 v237, 31, v96
	v_lshlrev_b64 v[236:237], 12, v[236:237]
	v_lshl_add_u64 v[236:237], s[48:49], 0, v[236:237]
	v_lshl_add_u64 v[236:237], v[236:237], 0, v[72:73]
	v_lshl_add_u64 v[236:237], v[236:237], 0, v[64:65]
	v_mov_b32_e32 v238, v156
	v_ashrrev_i32_e32 v239, 31, v156
	v_lshlrev_b64 v[238:239], 12, v[238:239]
	v_lshl_add_u64 v[238:239], s[48:49], 0, v[238:239]
	v_lshl_add_u64 v[238:239], v[238:239], 0, v[72:73]
	v_lshl_add_u64 v[238:239], v[238:239], 0, v[64:65]
	v_mov_b32_e32 v242, v158
	v_ashrrev_i32_e32 v243, 31, v158
	v_lshlrev_b64 v[242:243], 12, v[242:243]
	v_lshl_add_u64 v[242:243], s[48:49], 0, v[242:243]
	v_lshl_add_u64 v[242:243], v[242:243], 0, v[72:73]
	v_lshl_add_u64 v[242:243], v[242:243], 0, v[64:65]
	v_mov_b32_e32 v244, v74
	v_ashrrev_i32_e32 v245, 31, v74
	v_lshlrev_b64 v[244:245], 12, v[244:245]
	v_lshl_add_u64 v[244:245], s[48:49], 0, v[244:245]
	v_lshl_add_u64 v[244:245], v[244:245], 0, v[72:73]
	v_lshl_add_u64 v[244:245], v[244:245], 0, v[64:65]
	global_load_dwordx4 v[170:173], v[236:237], off
	global_load_dwordx4 v[174:177], v[236:237], off offset:64
	global_load_dwordx4 v[178:181], v[236:237], off offset:128
	global_load_dwordx4 v[182:185], v[236:237], off offset:192
	global_load_dwordx4 v[186:189], v[238:239], off
	global_load_dwordx4 v[190:193], v[238:239], off offset:64
	global_load_dwordx4 v[194:197], v[238:239], off offset:128
	global_load_dwordx4 v[198:201], v[238:239], off offset:192
	global_load_dwordx4 v[202:205], v[242:243], off
	global_load_dwordx4 v[206:209], v[242:243], off offset:64
	global_load_dwordx4 v[210:213], v[242:243], off offset:128
	global_load_dwordx4 v[214:217], v[242:243], off offset:192
	global_load_dwordx4 v[218:221], v[244:245], off
	global_load_dwordx4 v[222:225], v[244:245], off offset:64
	global_load_dwordx4 v[228:231], v[244:245], off offset:128
	global_load_dwordx4 v[232:235], v[244:245], off offset:192
	v_mfma_f32_16x16x32_bf16 v[88:91], v[44:47], v[144:147], v[112:115]
	s_waitcnt vmcnt(15)
	v_pk_mul_f32 v[170:171], v[170:171], s[16:17] op_sel_hi:[1,0]
	v_mfma_f32_16x16x32_bf16 v[96:99], v[36:39], v[144:147], v[120:123]
	v_mul_f32_e64 v172, v172, s16
	v_mul_f32_e64 v173, v173, s16
	s_waitcnt vmcnt(14)
	v_pk_mul_f32 v[174:175], v[174:175], s[16:17] op_sel_hi:[1,0]
	v_pk_mul_f32 v[176:177], v[176:177], s[16:17] op_sel_hi:[1,0]
	v_mfma_f32_16x16x32_bf16 v[92:95], v[40:43], v[144:147], v[116:119]
	s_waitcnt vmcnt(13)
	v_mul_f32_e64 v178, v178, s16
	v_mul_f32_e64 v179, v179, s16
	v_pk_mul_f32 v[180:181], v[180:181], s[16:17] op_sel_hi:[1,0]
	v_pk_fma_f32 v[88:89], v[88:89], v[20:21], v[170:171]
	v_mfma_f32_16x16x32_bf16 v[104:107], v[32:35], v[144:147], v[124:127]
	v_fma_f32 v90, v90, v22, v172
	v_fma_f32 v91, v91, v23, v173
	v_pk_fma_f32 v[92:93], v[92:93], v[0:1], v[174:175]
	v_pk_fma_f32 v[94:95], v[94:95], v[2:3], v[176:177]
	v_pk_fma_f32 v[96:97], v[96:97], v[12:13], v[178:179]
	v_pk_fma_f32 v[98:99], v[98:99], v[14:15], v[180:181]
	v_mfma_f32_16x16x32_bf16 v[116:119], v[44:47], v[148:151], v[128:131]
	s_waitcnt vmcnt(12)
	v_pk_mul_f32 v[182:183], v[182:183], s[16:17] op_sel_hi:[1,0]
	v_pk_mul_f32 v[184:185], v[184:185], s[16:17] op_sel_hi:[1,0]
	v_pk_fma_f32 v[170:171], v[104:105], v[16:17], v[182:183]
	v_pk_fma_f32 v[172:173], v[106:107], v[18:19], v[184:185]
	global_store_dwordx4 v[236:237], v[88:91], off
	global_store_dwordx4 v[236:237], v[92:95], off offset:64
	global_store_dwordx4 v[236:237], v[96:99], off offset:128
	global_store_dwordx4 v[236:237], v[170:173], off offset:192
	v_mfma_f32_16x16x32_bf16 v[124:127], v[40:43], v[148:151], v[132:135]
	v_mfma_f32_16x16x32_bf16 v[92:95], v[36:39], v[148:151], v[136:139]
	s_waitcnt vmcnt(15)
	v_pk_mul_f32 v[186:187], v[186:187], s[16:17] op_sel_hi:[1,0]
	v_mfma_f32_16x16x32_bf16 v[84:87], v[32:35], v[148:151], v[84:87]
	v_mul_f32_e64 v188, v188, s16
	v_mul_f32_e64 v189, v189, s16
	s_waitcnt vmcnt(14)
	v_pk_mul_f32 v[190:191], v[190:191], s[16:17] op_sel_hi:[1,0]
	v_pk_mul_f32 v[192:193], v[192:193], s[16:17] op_sel_hi:[1,0]
	s_waitcnt vmcnt(13)
	v_pk_mul_f32 v[194:195], v[194:195], s[16:17] op_sel_hi:[1,0]
	v_pk_mul_f32 v[196:197], v[196:197], s[16:17] op_sel_hi:[1,0]
	s_waitcnt vmcnt(12)
	v_pk_mul_f32 v[198:199], v[198:199], s[16:17] op_sel_hi:[1,0]
	v_pk_mul_f32 v[200:201], v[200:201], s[16:17] op_sel_hi:[1,0]
	v_pk_fma_f32 v[186:187], v[116:117], v[20:21], v[186:187]
	v_pk_fma_f32 v[188:189], v[118:119], v[22:23], v[188:189]
	v_pk_fma_f32 v[190:191], v[124:125], v[0:1], v[190:191]
	v_pk_fma_f32 v[192:193], v[126:127], v[2:3], v[192:193]
	v_pk_fma_f32 v[92:93], v[92:93], v[12:13], v[194:195]
	v_pk_fma_f32 v[94:95], v[94:95], v[14:15], v[196:197]
	v_pk_fma_f32 v[84:85], v[84:85], v[16:17], v[198:199]
	v_pk_fma_f32 v[86:87], v[86:87], v[18:19], v[200:201]
	global_store_dwordx4 v[238:239], v[186:189], off
	global_store_dwordx4 v[238:239], v[190:193], off offset:64
	global_store_dwordx4 v[238:239], v[92:95], off offset:128
	global_store_dwordx4 v[238:239], v[84:87], off offset:192
	v_mfma_f32_16x16x32_bf16 v[174:177], v[44:47], v[52:55], v[140:143]
	v_mfma_f32_16x16x32_bf16 v[186:189], v[40:43], v[52:55], v[152:155]
	v_mfma_f32_16x16x32_bf16 v[60:63], v[36:39], v[52:55], v[60:63]
	v_mfma_f32_16x16x32_bf16 v[52:55], v[32:35], v[52:55], v[56:59]
	v_mfma_f32_16x16x32_bf16 v[44:47], v[44:47], v[28:31], v[48:51]
	s_waitcnt vmcnt(15)
	v_pk_mul_f32 v[56:57], v[202:203], s[16:17] op_sel_hi:[1,0]
	v_pk_mul_f32 v[58:59], v[204:205], s[16:17] op_sel_hi:[1,0]
	s_waitcnt vmcnt(14)
	v_pk_mul_f32 v[202:203], v[206:207], s[16:17] op_sel_hi:[1,0]
	v_pk_mul_f32 v[204:205], v[208:209], s[16:17] op_sel_hi:[1,0]
	s_waitcnt vmcnt(13)
	v_pk_mul_f32 v[206:207], v[210:211], s[16:17] op_sel_hi:[1,0]
	v_pk_mul_f32 v[208:209], v[212:213], s[16:17] op_sel_hi:[1,0]
	s_waitcnt vmcnt(12)
	v_pk_mul_f32 v[210:211], v[214:215], s[16:17] op_sel_hi:[1,0]
	v_pk_mul_f32 v[212:213], v[216:217], s[16:17] op_sel_hi:[1,0]
	v_pk_fma_f32 v[56:57], v[174:175], v[20:21], v[56:57]
	v_pk_fma_f32 v[58:59], v[176:177], v[22:23], v[58:59]
	v_pk_fma_f32 v[202:203], v[186:187], v[0:1], v[202:203]
	v_pk_fma_f32 v[204:205], v[188:189], v[2:3], v[204:205]
	v_pk_fma_f32 v[60:61], v[60:61], v[12:13], v[206:207]
	v_pk_fma_f32 v[62:63], v[62:63], v[14:15], v[208:209]
	v_pk_fma_f32 v[52:53], v[52:53], v[16:17], v[210:211]
	v_pk_fma_f32 v[54:55], v[54:55], v[18:19], v[212:213]
	global_store_dwordx4 v[242:243], v[56:59], off
	global_store_dwordx4 v[242:243], v[202:205], off offset:64
	global_store_dwordx4 v[242:243], v[60:63], off offset:128
	global_store_dwordx4 v[242:243], v[52:55], off offset:192
	v_mfma_f32_16x16x32_bf16 v[24:27], v[40:43], v[28:31], v[24:27]
	v_mfma_f32_16x16x32_bf16 v[4:7], v[36:39], v[28:31], v[4:7]
	s_add_i32 s17, s17, s34
	s_cmpk_gt_i32 s2, 0x9f
	s_waitcnt vmcnt(13)
	v_pk_mul_f32 v[36:37], v[228:229], s[16:17] op_sel_hi:[1,0]
	v_mfma_f32_16x16x32_bf16 v[8:11], v[32:35], v[28:31], v[8:11]
	v_mul_f32_e64 v28, v218, s16
	v_mul_f32_e64 v29, v219, s16
	v_pk_mul_f32 v[30:31], v[220:221], s[16:17] op_sel_hi:[1,0]
	v_pk_mul_f32 v[32:33], v[222:223], s[16:17] op_sel_hi:[1,0]
	v_pk_mul_f32 v[34:35], v[224:225], s[16:17] op_sel_hi:[1,0]
	v_pk_mul_f32 v[38:39], v[230:231], s[16:17] op_sel_hi:[1,0]
	s_waitcnt vmcnt(12)
	v_pk_mul_f32 v[232:233], v[232:233], s[16:17] op_sel_hi:[1,0]
	v_pk_mul_f32 v[234:235], v[234:235], s[16:17] op_sel_hi:[1,0]
	v_pk_fma_f32 v[20:21], v[44:45], v[20:21], v[28:29]
	v_pk_fma_f32 v[22:23], v[46:47], v[22:23], v[30:31]
	v_pk_fma_f32 v[0:1], v[24:25], v[0:1], v[32:33]
	v_pk_fma_f32 v[2:3], v[26:27], v[2:3], v[34:35]
	v_pk_fma_f32 v[4:5], v[4:5], v[12:13], v[36:37]
	v_pk_fma_f32 v[6:7], v[6:7], v[14:15], v[38:39]
	v_pk_fma_f32 v[8:9], v[8:9], v[16:17], v[232:233]
	v_pk_fma_f32 v[10:11], v[10:11], v[18:19], v[234:235]
	global_store_dwordx4 v[244:245], v[20:23], off
	global_store_dwordx4 v[244:245], v[0:3], off offset:64
	global_store_dwordx4 v[244:245], v[4:7], off offset:128
	global_store_dwordx4 v[244:245], v[8:11], off offset:192
	s_cbranch_scc0 .LBB0_3062
